# in-proj GEMM loop: LDS-DMA pieces per phase 4/4/4/4 (S_A(0,0) to phase 3, S_A(1,0) to next phase 1; waits 8/6/8/6)
# baseline (speedup 1.0000x reference)
; #define PG8_STAGE(bufoff, gbase, voff) do { _Pragma("unroll") for (int _i = 0; _i < 2; ++_i) \
;         __builtin_amdgcn_global_load_lds((const unsigned*)((const char*)(gbase) + (voff)[_i]), (LAS unsigned*)(lds + (bufoff) + ldsw + _i * 8192), 16, 0, 0); } while (0)
; #define PG8_LDA(dst, b, h) do { _Pragma("unroll") for (int m = 0; m < 4; ++m) _Pragma("unroll") for (int k = 0; k < 2; ++k) dst[m][k] = *(const LAS bf16x8*)(lds + PG8_SA(b, h) + aoff + m * 2048 + k * 1024); } while (0)
; #define PG8_LDB(dst, b, h) do { _Pragma("unroll") for (int n = 0; n < 2; ++n) _Pragma("unroll") for (int k = 0; k < 2; ++k) dst[n][k] = *(const LAS bf16x8*)(lds + PG8_SB(b, h) + boff + n * 2048 + k * 1024); } while (0)
; #define PG8_WAIT_V(n) asm volatile("s_waitcnt vmcnt(" #n ")" ::: "memory")
; #define PG8_WAIT_L(n) asm volatile("s_waitcnt lgkmcnt(" #n ")" ::: "memory")
; #define PG8_BAR __builtin_amdgcn_s_barrier()
; #define PG8_SCHED __builtin_amdgcn_sched_barrier(0)
; template <class Epi>
; __device__ __forceinline__ void gemm_phase(LAS unsigned char* lds, const Gemm g, const StaticOrder& S, const Epi& E, const int tid) {
;     ...
;         for (int t = 0; t < nt; t += 2) {
;             const bool last = (t == nt - 2);
;             const char* a1 = cA + (size_t)(t + 1) * kstep;
;             const char* a2 = last ? nA : cA + (size_t)(t + 2) * kstep; const char* b2 = last ? nB : cB + (size_t)(t + 2) * kstep;
;             const char* a3 = a2 + kstep; const char* b3 = b2 + kstep;
;             if constexpr (Epi::MID) { if (t == 16 || t == 32) { int fr_ = fr, fq_ = fq, wr_ = wr, wc_ = wc;
;                 asm volatile("" : "+v"(fr_), "+v"(fq_)); asm volatile("" : "+s"(wr_), "+s"(wc_));
;                 E.mid(acc, cur, t >> 4, wr_, wc_, fr_, fq_); PG8_WAIT_V(0); PG8_SCHED; } }
;             PG8_LDB(B0, 0, 0); PG8_LDB(B1, 0, 1); PG8_SCHED; PG8_LDA(At, 0, 0); PG8_STAGE(PG8_SA(1, 1), a1 + hstep, voffA);
;             PG8_WAIT_V(8); PG8_WAIT_L(0); PG8_BAR; PG8_MMA(0, 0, At, B0); PG8_MMA(0, 1, At, B1); PG8_BAR; PG8_SCHED;
;             PG8_LDA(At, 0, 1); PG8_STAGE(PG8_SB(0, 0), b2, voffB); PG8_STAGE(PG8_SB(0, 1), b2 + hstep, voffB); PG8_STAGE(PG8_SA(0, 0), a2, voffA);
;             PG8_WAIT_V(8); PG8_WAIT_L(0); PG8_BAR; PG8_MMA(1, 0, At, B0); PG8_MMA(1, 1, At, B1); PG8_BAR; PG8_SCHED;
.LBB0_214:
	s_add_u32 s21, s44, 0xfff80080
	s_addc_u32 s29, s45, -1
	s_add_i32 s31, 0, 0x10000
	s_cmp_eq_u32 s20, 28
	s_cselect_b32 s49, s2, s29
	s_cselect_b32 s48, s3, s21
	s_cselect_b32 s47, s4, s13
	s_cselect_b32 s46, s5, s10
	s_add_i32 s21, 0, 0x14000
	v_add_u32_e32 v140, s31, v187
	v_add_u32_e32 v156, s21, v187
	s_waitcnt lgkmcnt(0)
	ds_read_b128 v[128:131], v140
	ds_read_b128 v[132:135], v140 offset:1024
	ds_read_b128 v[136:139], v140 offset:2048
	ds_read_b128 v[140:143], v140 offset:3072
	ds_read_b128 v[144:147], v156
	ds_read_b128 v[148:151], v156 offset:1024
	ds_read_b128 v[152:155], v156 offset:2048
	ds_read_b128 v[156:159], v156 offset:3072
	s_add_u32 s100, s44, 0xfff80000
	s_addc_u32 s101, s45, -1
	v_lshl_add_u64 v[220:221], s[100:101], 0, v[192:193]
	s_mov_b32 m0, s94
	s_nop 0
	global_load_lds_dwordx4 v[220:221], off
	v_lshl_add_u64 v[220:221], s[100:101], 0, v[196:197]
	s_mov_b32 m0, s95
	s_nop 0
	global_load_lds_dwordx4 v[220:221], off
	v_lshl_add_u64 v[220:221], s[44:45], 0, v[200:201]
	s_add_i32 m0, s37, 0xc000
	ds_read_b128 v[160:163], v191
	ds_read_b128 v[164:167], v191 offset:1024
	ds_read_b128 v[168:171], v191 offset:2048
	ds_read_b128 v[172:175], v191 offset:3072
	ds_read_b128 v[204:207], v191 offset:4096
	ds_read_b128 v[208:211], v191 offset:5120
	ds_read_b128 v[212:215], v191 offset:6144
	ds_read_b128 v[216:219], v191 offset:7168
	global_load_lds_dwordx4 v[220:221], off
	v_lshl_add_u64 v[220:221], s[44:45], 0, v[202:203]
	s_add_i32 m0, s37, 0xe000
	s_nop 0
	global_load_lds_dwordx4 v[220:221], off
	s_waitcnt vmcnt(8)
	s_waitcnt lgkmcnt(0)
	s_barrier
	s_setprio 1
	s_waitcnt lgkmcnt(0)
	v_mfma_f32_16x16x32_bf16 v[124:127], v[128:131], v[160:163], v[124:127]
	v_mfma_f32_16x16x32_bf16 v[108:111], v[136:139], v[160:163], v[108:111]
	v_mfma_f32_16x16x32_bf16 v[116:119], v[128:131], v[168:171], v[116:119]
	v_mfma_f32_16x16x32_bf16 v[100:103], v[136:139], v[168:171], v[100:103]
	v_mfma_f32_16x16x32_bf16 v[92:95], v[128:131], v[204:207], v[92:95]
	v_mfma_f32_16x16x32_bf16 v[76:79], v[136:139], v[204:207], v[76:79]
	v_mfma_f32_16x16x32_bf16 v[84:87], v[128:131], v[212:215], v[84:87]
	v_mfma_f32_16x16x32_bf16 v[68:71], v[136:139], v[212:215], v[68:71]
	v_mfma_f32_16x16x32_bf16 v[124:127], v[132:135], v[164:167], v[124:127]
	v_mfma_f32_16x16x32_bf16 v[108:111], v[140:143], v[164:167], v[108:111]
	v_mfma_f32_16x16x32_bf16 v[116:119], v[132:135], v[172:175], v[116:119]
	v_mfma_f32_16x16x32_bf16 v[100:103], v[140:143], v[172:175], v[100:103]
	v_mfma_f32_16x16x32_bf16 v[92:95], v[132:135], v[208:211], v[92:95]
	v_mfma_f32_16x16x32_bf16 v[76:79], v[140:143], v[208:211], v[76:79]
	v_mfma_f32_16x16x32_bf16 v[84:87], v[132:135], v[216:219], v[84:87]
	v_mfma_f32_16x16x32_bf16 v[68:71], v[140:143], v[216:219], v[68:71]
	s_setprio 0
	s_setprio 1
	v_mfma_f32_16x16x32_bf16 v[120:123], v[144:147], v[160:163], v[120:123]
	v_mfma_f32_16x16x32_bf16 v[104:107], v[152:155], v[160:163], v[104:107]
	v_mfma_f32_16x16x32_bf16 v[112:115], v[144:147], v[168:171], v[112:115]
	v_mfma_f32_16x16x32_bf16 v[96:99], v[152:155], v[168:171], v[96:99]
	v_mfma_f32_16x16x32_bf16 v[88:91], v[144:147], v[204:207], v[88:91]
	v_mfma_f32_16x16x32_bf16 v[72:75], v[152:155], v[204:207], v[72:75]
	v_mfma_f32_16x16x32_bf16 v[80:83], v[144:147], v[212:215], v[80:83]
	v_mfma_f32_16x16x32_bf16 v[64:67], v[152:155], v[212:215], v[64:67]
	v_mfma_f32_16x16x32_bf16 v[120:123], v[148:151], v[164:167], v[120:123]
	v_mfma_f32_16x16x32_bf16 v[104:107], v[156:159], v[164:167], v[104:107]
	v_mfma_f32_16x16x32_bf16 v[112:115], v[148:151], v[172:175], v[112:115]
	v_mfma_f32_16x16x32_bf16 v[96:99], v[156:159], v[172:175], v[96:99]
	v_mfma_f32_16x16x32_bf16 v[88:91], v[148:151], v[208:211], v[88:91]
	v_mfma_f32_16x16x32_bf16 v[72:75], v[156:159], v[208:211], v[72:75]
	v_mfma_f32_16x16x32_bf16 v[80:83], v[148:151], v[216:219], v[80:83]
	v_mfma_f32_16x16x32_bf16 v[64:67], v[156:159], v[216:219], v[64:67]
	s_setprio 0
	s_barrier
	s_add_i32 s29, s31, s62
	v_lshl_add_u64 v[220:221], s[46:47], 0, v[194:195]
	s_mov_b32 m0, s29
	ds_read_b128 v[160:163], v191 offset:16384
	ds_read_b128 v[164:167], v191 offset:17408
	ds_read_b128 v[168:171], v191 offset:18432
	ds_read_b128 v[172:175], v191 offset:19456
	ds_read_b128 v[204:207], v191 offset:20480
	ds_read_b128 v[208:211], v191 offset:21504
	ds_read_b128 v[212:215], v191 offset:22528
	ds_read_b128 v[216:219], v191 offset:23552
	global_load_lds_dwordx4 v[220:221], off
	s_add_i32 m0, s29, 0x2000
	s_add_u32 s42, s46, 0x80000
	v_lshl_add_u64 v[222:223], s[46:47], 0, v[198:199]
	s_addc_u32 s43, s47, 0
	s_add_i32 s21, s21, s62
	global_load_lds_dwordx4 v[222:223], off
	v_lshl_add_u64 v[224:225], s[42:43], 0, v[194:195]
	s_mov_b32 m0, s21
	v_lshl_add_u64 v[238:239], s[48:49], 0, v[196:197]
	global_load_lds_dwordx4 v[224:225], off
	v_lshl_add_u64 v[224:225], s[42:43], 0, v[198:199]
	s_add_i32 m0, s21, 0x2000
	s_nop 0
	global_load_lds_dwordx4 v[224:225], off
	v_lshl_add_u64 v[224:225], s[48:49], 0, v[192:193]
	s_waitcnt vmcnt(6)
	s_waitcnt lgkmcnt(0)
	s_barrier
; #define PG8_STAGE(bufoff, gbase, voff) do { _Pragma("unroll") for (int _i = 0; _i < 2; ++_i) \
;         __builtin_amdgcn_global_load_lds((const unsigned*)((const char*)(gbase) + (voff)[_i]), (LAS unsigned*)(lds + (bufoff) + ldsw + _i * 8192), 16, 0, 0); } while (0)
; #define PG8_LDA(dst, b, h) do { _Pragma("unroll") for (int m = 0; m < 4; ++m) _Pragma("unroll") for (int k = 0; k < 2; ++k) dst[m][k] = *(const LAS bf16x8*)(lds + PG8_SA(b, h) + aoff + m * 2048 + k * 1024); } while (0)
; #define PG8_LDB(dst, b, h) do { _Pragma("unroll") for (int n = 0; n < 2; ++n) _Pragma("unroll") for (int k = 0; k < 2; ++k) dst[n][k] = *(const LAS bf16x8*)(lds + PG8_SB(b, h) + boff + n * 2048 + k * 1024); } while (0)
; #define PG8_MMA(ai, bj, At, Bt) do { __builtin_amdgcn_s_setprio(1); _Pragma("unroll") for (int m = 0; m < 4; ++m) _Pragma("unroll") for (int n = 0; n < 2; ++n) _Pragma("unroll") for (int k = 0; k < 2; ++k) \
;         acc[ai][bj][m][n] = __builtin_amdgcn_mfma_f32_16x16x32_bf16(Bt[n][k], At[m][k], acc[ai][bj][m][n], 0, 0, 0); __builtin_amdgcn_s_setprio(0); } while (0)
; #define PG8_WAIT_V(n) asm volatile("s_waitcnt vmcnt(" #n ")" ::: "memory")
; #define PG8_WAIT_L(n) asm volatile("s_waitcnt lgkmcnt(" #n ")" ::: "memory")
; #define PG8_BAR __builtin_amdgcn_s_barrier()
; #define PG8_SCHED __builtin_amdgcn_sched_barrier(0)
; template <class Epi>
; __device__ __forceinline__ void gemm_phase(LAS unsigned char* lds, const Gemm g, const StaticOrder& S, const Epi& E, const int tid) {
;     ...
;             PG8_WAIT_V(8); PG8_WAIT_L(0); PG8_BAR; PG8_MMA(1, 0, At, B0); PG8_MMA(1, 1, At, B1); PG8_BAR; PG8_SCHED;
;             PG8_LDB(B0, 1, 0); PG8_LDB(B1, 1, 1); PG8_SCHED; PG8_LDA(At, 1, 0); PG8_STAGE(PG8_SA(0, 1), a2 + hstep, voffA);
;             PG8_WAIT_V(8); PG8_WAIT_L(0); PG8_BAR; PG8_MMA(0, 0, At, B0); PG8_MMA(0, 1, At, B1); PG8_BAR; PG8_SCHED;
;             PG8_LDA(At, 1, 1); PG8_STAGE(PG8_SB(1, 0), b3, voffB); PG8_STAGE(PG8_SB(1, 1), b3 + hstep, voffB); PG8_STAGE(PG8_SA(1, 0), a3, voffA);
	s_setprio 1
	s_waitcnt lgkmcnt(0)
	v_mfma_f32_16x16x32_bf16 v[60:63], v[128:131], v[160:163], v[60:63]
	v_mfma_f32_16x16x32_bf16 v[44:47], v[136:139], v[160:163], v[44:47]
	v_mfma_f32_16x16x32_bf16 v[52:55], v[128:131], v[168:171], v[52:55]
	v_mfma_f32_16x16x32_bf16 v[36:39], v[136:139], v[168:171], v[36:39]
	v_mfma_f32_16x16x32_bf16 v[28:31], v[128:131], v[204:207], v[28:31]
	v_mfma_f32_16x16x32_bf16 v[12:15], v[136:139], v[204:207], v[12:15]
	v_mfma_f32_16x16x32_bf16 v[20:23], v[128:131], v[212:215], v[20:23]
	v_mfma_f32_16x16x32_bf16 v[4:7], v[136:139], v[212:215], v[4:7]
	v_mfma_f32_16x16x32_bf16 v[60:63], v[132:135], v[164:167], v[60:63]
	v_mfma_f32_16x16x32_bf16 v[44:47], v[140:143], v[164:167], v[44:47]
	v_mfma_f32_16x16x32_bf16 v[52:55], v[132:135], v[172:175], v[52:55]
	v_mfma_f32_16x16x32_bf16 v[36:39], v[140:143], v[172:175], v[36:39]
	v_mfma_f32_16x16x32_bf16 v[28:31], v[132:135], v[208:211], v[28:31]
	v_mfma_f32_16x16x32_bf16 v[12:15], v[140:143], v[208:211], v[12:15]
	v_mfma_f32_16x16x32_bf16 v[20:23], v[132:135], v[216:219], v[20:23]
	v_mfma_f32_16x16x32_bf16 v[4:7], v[140:143], v[216:219], v[4:7]
	s_setprio 0
	s_setprio 1
	v_mfma_f32_16x16x32_bf16 v[56:59], v[144:147], v[160:163], v[56:59]
	v_mfma_f32_16x16x32_bf16 v[40:43], v[152:155], v[160:163], v[40:43]
	v_mfma_f32_16x16x32_bf16 v[48:51], v[144:147], v[168:171], v[48:51]
	v_mfma_f32_16x16x32_bf16 v[32:35], v[152:155], v[168:171], v[32:35]
	v_mfma_f32_16x16x32_bf16 v[24:27], v[144:147], v[204:207], v[24:27]
	v_mfma_f32_16x16x32_bf16 v[8:11], v[152:155], v[204:207], v[8:11]
	v_mfma_f32_16x16x32_bf16 v[16:19], v[144:147], v[212:215], v[16:19]
	v_mfma_f32_16x16x32_bf16 v[0:3], v[152:155], v[212:215], v[0:3]
	v_mfma_f32_16x16x32_bf16 v[56:59], v[148:151], v[164:167], v[56:59]
	v_mfma_f32_16x16x32_bf16 v[40:43], v[156:159], v[164:167], v[40:43]
	v_mfma_f32_16x16x32_bf16 v[48:51], v[148:151], v[172:175], v[48:51]
	v_mfma_f32_16x16x32_bf16 v[32:35], v[156:159], v[172:175], v[32:35]
	v_mfma_f32_16x16x32_bf16 v[24:27], v[148:151], v[208:211], v[24:27]
	v_mfma_f32_16x16x32_bf16 v[8:11], v[156:159], v[208:211], v[8:11]
	v_mfma_f32_16x16x32_bf16 v[16:19], v[148:151], v[216:219], v[16:19]
	v_mfma_f32_16x16x32_bf16 v[0:3], v[156:159], v[216:219], v[0:3]
	s_setprio 0
	s_barrier
	s_add_i32 s21, 0, 0x18000
	s_add_i32 s29, 0, 0x1c000
	v_add_u32_e32 v140, s21, v187
	v_add_u32_e32 v156, s29, v187
	ds_read_b128 v[128:131], v140
	ds_read_b128 v[132:135], v140 offset:1024
	ds_read_b128 v[136:139], v140 offset:2048
	ds_read_b128 v[140:143], v140 offset:3072
	ds_read_b128 v[144:147], v156
	ds_read_b128 v[148:151], v156 offset:1024
	ds_read_b128 v[152:155], v156 offset:2048
	ds_read_b128 v[156:159], v156 offset:3072
	s_add_u32 s42, s48, 0x80000
	s_addc_u32 s43, s49, 0
	s_mov_b32 m0, s37
	s_nop 0
	global_load_lds_dwordx4 v[224:225], off
	s_mov_b32 m0, s63
	s_nop 0
	global_load_lds_dwordx4 v[238:239], off
	s_mov_b32 m0, s58
	v_lshl_add_u64 v[240:241], s[42:43], 0, v[192:193]
	ds_read_b128 v[160:163], v191 offset:32768
	ds_read_b128 v[164:167], v191 offset:33792
	ds_read_b128 v[168:171], v191 offset:34816
	ds_read_b128 v[172:175], v191 offset:35840
	ds_read_b128 v[204:207], v191 offset:36864
	ds_read_b128 v[208:211], v191 offset:37888
	ds_read_b128 v[212:215], v191 offset:38912
	ds_read_b128 v[216:219], v191 offset:39936
	global_load_lds_dwordx4 v[240:241], off
	v_lshl_add_u64 v[240:241], s[42:43], 0, v[196:197]
	s_mov_b32 m0, s59
	s_nop 0
	global_load_lds_dwordx4 v[240:241], off
	s_waitcnt vmcnt(8)
	s_waitcnt lgkmcnt(0)
	s_barrier
; #define PG8_STAGE(bufoff, gbase, voff) do { _Pragma("unroll") for (int _i = 0; _i < 2; ++_i) \
;         __builtin_amdgcn_global_load_lds((const unsigned*)((const char*)(gbase) + (voff)[_i]), (LAS unsigned*)(lds + (bufoff) + ldsw + _i * 8192), 16, 0, 0); } while (0)
; #define PG8_LDA(dst, b, h) do { _Pragma("unroll") for (int m = 0; m < 4; ++m) _Pragma("unroll") for (int k = 0; k < 2; ++k) dst[m][k] = *(const LAS bf16x8*)(lds + PG8_SA(b, h) + aoff + m * 2048 + k * 1024); } while (0)
; #define PG8_MMA(ai, bj, At, Bt) do { __builtin_amdgcn_s_setprio(1); _Pragma("unroll") for (int m = 0; m < 4; ++m) _Pragma("unroll") for (int n = 0; n < 2; ++n) _Pragma("unroll") for (int k = 0; k < 2; ++k) \
;         acc[ai][bj][m][n] = __builtin_amdgcn_mfma_f32_16x16x32_bf16(Bt[n][k], At[m][k], acc[ai][bj][m][n], 0, 0, 0); __builtin_amdgcn_s_setprio(0); } while (0)
; #define PG8_WAIT_V(n) asm volatile("s_waitcnt vmcnt(" #n ")" ::: "memory")
; #define PG8_WAIT_L(n) asm volatile("s_waitcnt lgkmcnt(" #n ")" ::: "memory")
; #define PG8_BAR __builtin_amdgcn_s_barrier()
; #define PG8_SCHED __builtin_amdgcn_sched_barrier(0)
; template <class Epi>
; __device__ __forceinline__ void gemm_phase(LAS unsigned char* lds, const Gemm g, const StaticOrder& S, const Epi& E, const int tid) {
;     ...
;             PG8_WAIT_V(8); PG8_WAIT_L(0); PG8_BAR; PG8_MMA(0, 0, At, B0); PG8_MMA(0, 1, At, B1); PG8_BAR; PG8_SCHED;
;             PG8_LDA(At, 1, 1); PG8_STAGE(PG8_SB(1, 0), b3, voffB); PG8_STAGE(PG8_SB(1, 1), b3 + hstep, voffB); PG8_STAGE(PG8_SA(1, 0), a3, voffA);
;             PG8_WAIT_V(8); PG8_WAIT_L(0); PG8_BAR; PG8_MMA(1, 0, At, B0); PG8_MMA(1, 1, At, B1); PG8_BAR; PG8_SCHED;
;         }
	s_setprio 1
	s_waitcnt lgkmcnt(0)
	v_mfma_f32_16x16x32_bf16 v[124:127], v[128:131], v[160:163], v[124:127]
	v_mfma_f32_16x16x32_bf16 v[108:111], v[136:139], v[160:163], v[108:111]
	v_mfma_f32_16x16x32_bf16 v[116:119], v[128:131], v[168:171], v[116:119]
	v_mfma_f32_16x16x32_bf16 v[100:103], v[136:139], v[168:171], v[100:103]
	v_mfma_f32_16x16x32_bf16 v[92:95], v[128:131], v[204:207], v[92:95]
	v_mfma_f32_16x16x32_bf16 v[76:79], v[136:139], v[204:207], v[76:79]
	v_mfma_f32_16x16x32_bf16 v[84:87], v[128:131], v[212:215], v[84:87]
	v_mfma_f32_16x16x32_bf16 v[68:71], v[136:139], v[212:215], v[68:71]
	v_mfma_f32_16x16x32_bf16 v[124:127], v[132:135], v[164:167], v[124:127]
	v_mfma_f32_16x16x32_bf16 v[108:111], v[140:143], v[164:167], v[108:111]
	v_mfma_f32_16x16x32_bf16 v[116:119], v[132:135], v[172:175], v[116:119]
	v_mfma_f32_16x16x32_bf16 v[100:103], v[140:143], v[172:175], v[100:103]
	v_mfma_f32_16x16x32_bf16 v[92:95], v[132:135], v[208:211], v[92:95]
	v_mfma_f32_16x16x32_bf16 v[76:79], v[140:143], v[208:211], v[76:79]
	v_mfma_f32_16x16x32_bf16 v[84:87], v[132:135], v[216:219], v[84:87]
	v_mfma_f32_16x16x32_bf16 v[68:71], v[140:143], v[216:219], v[68:71]
	s_setprio 0
	s_setprio 1
	v_mfma_f32_16x16x32_bf16 v[120:123], v[144:147], v[160:163], v[120:123]
	v_mfma_f32_16x16x32_bf16 v[104:107], v[152:155], v[160:163], v[104:107]
	v_mfma_f32_16x16x32_bf16 v[112:115], v[144:147], v[168:171], v[112:115]
	v_mfma_f32_16x16x32_bf16 v[96:99], v[152:155], v[168:171], v[96:99]
	v_mfma_f32_16x16x32_bf16 v[88:91], v[144:147], v[204:207], v[88:91]
	v_mfma_f32_16x16x32_bf16 v[72:75], v[152:155], v[204:207], v[72:75]
	v_mfma_f32_16x16x32_bf16 v[80:83], v[144:147], v[212:215], v[80:83]
	v_mfma_f32_16x16x32_bf16 v[64:67], v[152:155], v[212:215], v[64:67]
	v_mfma_f32_16x16x32_bf16 v[120:123], v[148:151], v[164:167], v[120:123]
	v_mfma_f32_16x16x32_bf16 v[104:107], v[156:159], v[164:167], v[104:107]
	v_mfma_f32_16x16x32_bf16 v[112:115], v[148:151], v[172:175], v[112:115]
	v_mfma_f32_16x16x32_bf16 v[96:99], v[156:159], v[172:175], v[96:99]
	v_mfma_f32_16x16x32_bf16 v[88:91], v[148:151], v[208:211], v[88:91]
	v_mfma_f32_16x16x32_bf16 v[72:75], v[156:159], v[208:211], v[72:75]
	v_mfma_f32_16x16x32_bf16 v[80:83], v[148:151], v[216:219], v[80:83]
	v_mfma_f32_16x16x32_bf16 v[64:67], v[156:159], v[216:219], v[64:67]
	s_setprio 0
	s_barrier
	s_add_i32 s21, s21, s62
	v_lshl_add_u64 v[220:221], v[220:221], 0, s[0:1]
	s_mov_b32 m0, s21
	ds_read_b128 v[160:163], v191 offset:49152
	ds_read_b128 v[164:167], v191 offset:50176
	ds_read_b128 v[168:171], v191 offset:51200
	ds_read_b128 v[172:175], v191 offset:52224
	ds_read_b128 v[204:207], v191 offset:53248
	ds_read_b128 v[208:211], v191 offset:54272
	ds_read_b128 v[212:215], v191 offset:55296
	ds_read_b128 v[216:219], v191 offset:56320
	global_load_lds_dwordx4 v[220:221], off
	s_add_i32 m0, s21, 0x2000
	s_add_u32 s42, s46, 0x80080
	v_lshl_add_u64 v[220:221], v[222:223], 0, s[0:1]
	s_addc_u32 s43, s47, 0
	s_add_i32 s21, s29, s62
	global_load_lds_dwordx4 v[220:221], off
	v_lshl_add_u64 v[220:221], s[42:43], 0, v[194:195]
	s_mov_b32 m0, s21
	s_nop 0
	global_load_lds_dwordx4 v[220:221], off
	v_lshl_add_u64 v[220:221], s[42:43], 0, v[198:199]
	s_add_i32 m0, s21, 0x2000
	s_nop 0
	global_load_lds_dwordx4 v[220:221], off
	s_waitcnt vmcnt(6)
	s_waitcnt lgkmcnt(0)
	s_barrier
	s_setprio 1
	s_waitcnt lgkmcnt(0)
	v_mfma_f32_16x16x32_bf16 v[60:63], v[128:131], v[160:163], v[60:63]
	v_mfma_f32_16x16x32_bf16 v[44:47], v[136:139], v[160:163], v[44:47]
	v_mfma_f32_16x16x32_bf16 v[52:55], v[128:131], v[168:171], v[52:55]
	v_mfma_f32_16x16x32_bf16 v[36:39], v[136:139], v[168:171], v[36:39]
	v_mfma_f32_16x16x32_bf16 v[28:31], v[128:131], v[204:207], v[28:31]
	v_mfma_f32_16x16x32_bf16 v[12:15], v[136:139], v[204:207], v[12:15]
	v_mfma_f32_16x16x32_bf16 v[20:23], v[128:131], v[212:215], v[20:23]
	v_mfma_f32_16x16x32_bf16 v[4:7], v[136:139], v[212:215], v[4:7]
	v_mfma_f32_16x16x32_bf16 v[60:63], v[132:135], v[164:167], v[60:63]
	v_mfma_f32_16x16x32_bf16 v[44:47], v[140:143], v[164:167], v[44:47]
	v_mfma_f32_16x16x32_bf16 v[52:55], v[132:135], v[172:175], v[52:55]
	v_mfma_f32_16x16x32_bf16 v[36:39], v[140:143], v[172:175], v[36:39]
	v_mfma_f32_16x16x32_bf16 v[28:31], v[132:135], v[208:211], v[28:31]
	v_mfma_f32_16x16x32_bf16 v[12:15], v[140:143], v[208:211], v[12:15]
	v_mfma_f32_16x16x32_bf16 v[20:23], v[132:135], v[216:219], v[20:23]
	v_mfma_f32_16x16x32_bf16 v[4:7], v[140:143], v[216:219], v[4:7]
	s_setprio 0
	s_setprio 1
	v_mfma_f32_16x16x32_bf16 v[56:59], v[144:147], v[160:163], v[56:59]
	v_mfma_f32_16x16x32_bf16 v[40:43], v[152:155], v[160:163], v[40:43]
	v_mfma_f32_16x16x32_bf16 v[48:51], v[144:147], v[168:171], v[48:51]
	v_mfma_f32_16x16x32_bf16 v[32:35], v[152:155], v[168:171], v[32:35]
	v_mfma_f32_16x16x32_bf16 v[24:27], v[144:147], v[204:207], v[24:27]
	v_mfma_f32_16x16x32_bf16 v[8:11], v[152:155], v[204:207], v[8:11]
	v_mfma_f32_16x16x32_bf16 v[16:19], v[144:147], v[212:215], v[16:19]
	v_mfma_f32_16x16x32_bf16 v[0:3], v[152:155], v[212:215], v[0:3]
	v_mfma_f32_16x16x32_bf16 v[56:59], v[148:151], v[164:167], v[56:59]
	v_mfma_f32_16x16x32_bf16 v[40:43], v[156:159], v[164:167], v[40:43]
	v_mfma_f32_16x16x32_bf16 v[48:51], v[148:151], v[172:175], v[48:51]
	v_mfma_f32_16x16x32_bf16 v[32:35], v[156:159], v[172:175], v[32:35]
	v_mfma_f32_16x16x32_bf16 v[24:27], v[148:151], v[208:211], v[24:27]
	v_mfma_f32_16x16x32_bf16 v[8:11], v[156:159], v[208:211], v[8:11]
	v_mfma_f32_16x16x32_bf16 v[16:19], v[148:151], v[216:219], v[16:19]
	v_mfma_f32_16x16x32_bf16 v[0:3], v[156:159], v[216:219], v[0:3]
	s_setprio 0
	s_barrier
	s_add_i32 s20, s20, 2
	s_add_u32 s44, s44, 0x100
	s_addc_u32 s45, s45, 0
	s_add_u32 s10, s10, 0x100
	s_addc_u32 s13, s13, 0
	s_cmp_gt_u32 s20, 29
	s_cbranch_scc0 .LBB0_214
	s_and_b64 vcc, exec, s[14:15]
	s_cbranch_vccz .LBB0_217
	s_barrier
